# GU phases: workgroups start in 4 groups offset by ~1.5us each so per-tile H store bursts do not coincide chip-wide
# baseline (speedup 1.0000x reference)
; #define LAS __attribute__((address_space(3)))
; #define PG8_STAGE(bufoff, gbase, voff) do { _Pragma("unroll") for (int _i = 0; _i < 2; ++_i) \
;         __builtin_amdgcn_global_load_lds((const unsigned*)((const char*)(gbase) + (voff)[_i]), (LAS unsigned*)(lds + (bufoff) + ldsw + _i * 8192), 16, 0, 0); } while (0)
; #define PG8_WAIT_V(n) asm volatile("s_waitcnt vmcnt(" #n ")" ::: "memory")
; #define PG8_BAR __builtin_amdgcn_s_barrier()
; template <class Epi>
; DI void gemm_phase(LAS unsigned char* lds, const int tid, const Gemm g, const StaticOrder& S, const Epi& E) {
;     const int wid = __builtin_amdgcn_readfirstlane(tid >> 6), lane = tid & 63, wr = wid >> 2, wc = wid & 3, fr = lane & 15, fq = lane >> 4;
;     const int K = g.K, nt = K / BK, lda = g.lda;
;     unsigned voffA[2], voffB[2];
; #pragma unroll
;     for (int i = 0; i < 2; ++i) { int R, C; stage_rc(tid * 16 + i * 8192, R, C); const int Rb = (R & ~31) + perm32(R & 31);
;         voffA[i] = (unsigned)(R * lda + C) * 2u; voffB[i] = (unsigned)(Rb * K + C) * 2u; }
;     const size_t kstep = (size_t)(BK * 2);
;     const size_t hstepA = (size_t)HALF * lda * 2, hstepB = (size_t)HALF * K * 2;
;     const size_t tstepA = 2 * hstepA, tstepB = 2 * hstepB;
;     const unsigned ldsw = (unsigned)wid * 1024u;
;     const int aoff = lds_byte(wr * 64 + fr, fq * 8), boff = lds_byte(wc * 32 + fr, fq * 8);
;     ...
;     Unit cur, nxt; int ui = 0;
;     if (!S.next(0, cur)) return;
;     f32x4 acc[2][2][4][2];
; #pragma unroll
;     for (int a = 0; a < 2; ++a)
; #pragma unroll
;         for (int b = 0; b < 2; ++b)
; #pragma unroll
;             for (int m = 0; m < 4; ++m)
; #pragma unroll
;                 for (int n = 0; n < 2; ++n) acc[a][b][m][n] = (f32x4){0.f, 0.f, 0.f, 0.f};
;     bf16x8 At[4][2], B0[2][2], B1[2][2];
;     const char* cA = (const char*)g.A + (size_t)cur.pm * tstepA; const char* cB = (const char*)g.Bt + (size_t)cur.pn * tstepB;
;     PG8_STAGE(PG8_SB(0, 0), cB, voffB); PG8_STAGE(PG8_SB(0, 1), cB + hstepB, voffB); PG8_STAGE(PG8_SA(0, 0), cA, voffA); PG8_STAGE(PG8_SA(0, 1), cA + hstepA, voffA);
;     if (wr == 1) PG8_BAR;
;     PG8_WAIT_V(2); PG8_BAR;
;     PG8_STAGE(PG8_SB(1, 0), cB + kstep, voffB); PG8_STAGE(PG8_SA(1, 0), cA + kstep, voffA); PG8_STAGE(PG8_SB(1, 1), cB + hstepB + kstep, voffB);
;     PG8_WAIT_V(6); PG8_BAR;
.LBB0_657:
	s_andn2_b64 vcc, exec, s[6:7]
	s_cbranch_vccnz .LBB0_674
	v_readlane_b32 s4, v253, 51
	s_waitcnt lgkmcnt(0)
	v_readlane_b32 s0, v253, 12
	v_mov_b32_e32 v6, v240
	v_readlane_b32 s6, v253, 53
	v_readlane_b32 s1, v253, 13
	s_mov_b32 s14, s6
	s_andn2_b64 vcc, exec, s[0:1]
	v_readfirstlane_b32 s4, v6
	v_readlane_b32 s5, v253, 52
	v_readlane_b32 s7, v253, 54
	s_cbranch_vccnz .LBB0_674
	v_readlane_b32 s100, v253, 0
	s_nop 3
	s_bfe_u32 s100, s100, 0x20003
	s_cmp_eq_u32 s100, 0
	s_cbranch_scc1 .Lgu_nodelay
.Lgu_dl:
	s_sleep 45
	s_sub_u32 s100, s100, 1
	s_cmp_lg_u32 s100, 0
	s_cbranch_scc1 .Lgu_dl
.Lgu_nodelay:
	v_lshlrev_b32_e32 v0, 4, v6
	v_add_u32_e32 v2, 0x2000, v0
	v_ashrrev_i32_e32 v3, 31, v2
	v_lshrrev_b32_e32 v3, 22, v3
	v_add_u32_e32 v3, v2, v3
	v_ashrrev_i32_e32 v7, 10, v3
	v_mul_i32_i24_e32 v3, 0x400, v7
	v_sub_u32_e32 v2, v2, v3
	v_lshrrev_b32_e32 v3, 4, v2
	v_bitop3_b32 v2, v3, v2, 32 bitop3:0x6c
	v_ashrrev_i32_e32 v3, 31, v2
	v_lshrrev_b32_e32 v3, 26, v3
	v_readlane_b32 s0, v255, 9
	v_add_u32_e32 v3, v2, v3
	v_lshlrev_b32_e32 v4, 3, v7
	s_mul_i32 s46, s0, 0x580000
	v_ashrrev_i32_e32 v8, 6, v3
	v_and_b32_e32 v4, -16, v4
	s_lshl_b64 s[0:1], s[46:47], 1
	v_add_u32_e32 v4, v8, v4
	s_add_u32 s15, s22, s0
	v_and_b32_e32 v5, 3, v8
	s_mov_b32 s0, 0x1fffe0
	v_lshrrev_b32_e32 v9, 2, v4
	v_lshlrev_b32_e32 v10, 1, v4
	v_and_b32_e32 v3, 0xc0, v3
	v_and_or_b32 v5, v4, s0, v5
	v_and_b32_e32 v9, 4, v9
	v_and_b32_e32 v10, 24, v10
	v_sub_u32_e32 v2, v2, v3
	v_or3_b32 v5, v5, v9, v10
	v_lshlrev_b32_e32 v9, 5, v7
	v_ashrrev_i16_sdwa v2, v244, sext(v2) dst_sel:DWORD dst_unused:UNUSED_PAD src0_sel:DWORD src1_sel:BYTE_0
	v_and_b32_e32 v10, 32, v9
	v_bfe_i32 v9, v2, 0, 16
	v_add_lshl_u32 v2, v10, v9, 1
	v_lshl_add_u32 v130, v5, 11, v2
	v_lshl_add_u32 v132, v4, 11, v2
	v_bfe_i32 v2, v6, 27, 1
	v_lshrrev_b32_e32 v2, 22, v2
	v_add_u32_e32 v2, v0, v2
	v_and_b32_e32 v2, 0xfffffc00, v2
	v_sub_u32_e32 v0, v0, v2
	v_lshrrev_b32_e32 v2, 4, v0
	v_ashrrev_i32_e32 v3, 31, v6
	v_bitop3_b32 v0, v2, v0, 32 bitop3:0x6c
	v_lshrrev_b32_e32 v3, 26, v3
	v_ashrrev_i32_e32 v2, 31, v0
	v_add_u32_e32 v3, v6, v3
	v_lshrrev_b32_e32 v2, 26, v2
	v_ashrrev_i32_e32 v11, 6, v3
	v_add_u32_e32 v2, v0, v2
	v_lshlrev_b32_e32 v3, 3, v11
	v_ashrrev_i32_e32 v10, 6, v2
	v_and_b32_e32 v3, -16, v3
	v_add_u32_e32 v3, v10, v3
	v_and_b32_e32 v4, 3, v10
	v_lshrrev_b32_e32 v5, 2, v3
	v_lshlrev_b32_e32 v12, 1, v3
	v_and_b32_e32 v2, 0xc0, v2
	s_addc_u32 s24, s23, s1
	s_ashr_i32 s6, s4, 6
	v_and_or_b32 v4, v3, s0, v4
	v_and_b32_e32 v5, 4, v5
	v_and_b32_e32 v12, 24, v12
	v_sub_u32_e32 v0, v0, v2
	s_ashr_i32 s5, s4, 8
	s_lshl_b32 s25, s6, 10
	v_or3_b32 v4, v4, v5, v12
	v_lshlrev_b32_e32 v5, 5, v11
	v_ashrrev_i16_sdwa v0, v244, sext(v0) dst_sel:DWORD dst_unused:UNUSED_PAD src0_sel:DWORD src1_sel:BYTE_0
	v_readlane_b32 s0, v253, 21
	v_and_b32_e32 v5, 32, v5
	v_bfe_i32 v12, v0, 0, 16
	v_readlane_b32 s1, v253, 22
	s_add_u32 s36, s15, s0
	v_add_lshl_u32 v2, v5, v12, 1
	s_addc_u32 s37, s24, s1
	s_add_i32 s30, s25, 0
	v_lshl_add_u32 v0, v4, 11, v2
	s_add_i32 m0, s30, 0x10000
	v_lshl_add_u32 v134, v3, 11, v2
	global_load_lds_dwordx4 v0, s[36:37]
	s_add_i32 m0, s30, 0x12000
	s_add_u32 s0, s36, 0x40000
	global_load_lds_dwordx4 v130, s[36:37]
	s_addc_u32 s1, s37, 0
	s_add_i32 m0, s30, 0x14000
	s_add_i32 s31, s30, 0x2000
	global_load_lds_dwordx4 v0, s[0:1]
	s_add_i32 m0, s30, 0x16000
	s_add_i32 s38, s30, 0x4000
	global_load_lds_dwordx4 v130, s[0:1]
	v_readlane_b32 s0, v254, 37
	s_mov_b32 m0, s30
	v_readlane_b32 s1, v254, 38
	s_add_i32 s39, s30, 0x6000
	v_mov_b32_e32 v131, v1
	s_cmp_eq_u32 s5, 1
	v_lshl_add_u64 v[2:3], s[36:37], 0, v[0:1]
	v_lshl_add_u64 v[4:5], s[36:37], 0, v[130:131]
	global_load_lds_dwordx4 v134, s[0:1]
	s_mov_b32 m0, s31
	s_nop 0
	global_load_lds_dwordx4 v132, s[0:1]
	v_readlane_b32 s0, v254, 39
	s_mov_b32 m0, s38
	v_readlane_b32 s1, v254, 40
	s_nop 4
	global_load_lds_dwordx4 v134, s[0:1]
	s_mov_b32 m0, s39
	s_nop 0
	global_load_lds_dwordx4 v132, s[0:1]
	s_cselect_b64 s[0:1], -1, 0
	s_cmp_lg_u32 s5, 1
	s_cbranch_scc1 .LBB0_661
	s_barrier
